# attention head loop: the three per-head z_c gate loads and the sink load hoisted to the loop top (latency hidden behind QK^T) instead of load-wait at each use; attention workgroups are now the phase-3
# speedup vs baseline: 1.0218x; 1.0056x over previous
.LBB0_834:
	v_lshl_add_u64 v[18:19], v[56:57], 0, s[28:29]
	v_add_co_u32_e32 v60, vcc, 0x13a43000, v18
	ds_read_b128 v[22:25], v66 offset:64
	s_nop 0
	v_addc_co_u32_e32 v61, vcc, 0, v19, vcc
	ds_read_b128 v[18:21], v66
	global_load_dwordx2 v[62:63], v[60:61], off offset:512
	global_load_dwordx2 v[88:89], v[60:61], off offset:544
	global_load_dwordx2 v[90:91], v[60:61], off offset:576
	global_load_dwordx2 v[92:93], v[60:61], off offset:608
	global_load_dword v86, v1, s[2:3]
	s_waitcnt lgkmcnt(0)
	v_mfma_f32_16x16x32_bf16 v[18:21], v[18:21], v[10:13], 0
	ds_read_b128 v[76:79], v74 offset:64
	v_mfma_f32_16x16x32_bf16 v[46:49], v[22:25], v[14:17], v[18:21]
	ds_read_b128 v[22:25], v67 offset:64
	s_nop 4
	ds_read_b128 v[18:21], v67
	s_waitcnt lgkmcnt(0)
	v_mfma_f32_16x16x32_bf16 v[18:21], v[18:21], v[10:13], 0
	v_cndmask_b32_e64 v46, v223, v46, s[0:1]
	v_cndmask_b32_e64 v47, v223, v47, s[38:39]
	v_cndmask_b32_e64 v48, v223, v48, s[40:41]
	v_mfma_f32_16x16x32_bf16 v[50:53], v[22:25], v[14:17], v[18:21]
	ds_read_b128 v[22:25], v68 offset:64
	v_cndmask_b32_e64 v49, v223, v49, s[42:43]
	s_nop 1
	ds_read_b128 v[18:21], v68
	s_waitcnt lgkmcnt(0)
	v_mfma_f32_16x16x32_bf16 v[18:21], v[18:21], v[10:13], 0
	s_nop 0
	v_cndmask_b32_e64 v50, v223, v50, s[44:45]
	v_cndmask_b32_e64 v51, v223, v51, s[46:47]
	v_cndmask_b32_e64 v52, v223, v52, s[48:49]
	v_mfma_f32_16x16x32_bf16 v[42:45], v[22:25], v[14:17], v[18:21]
	ds_read_b128 v[22:25], v69 offset:64
	v_cndmask_b32_e64 v53, v223, v53, s[50:51]
	s_nop 0
	ds_read_b128 v[18:21], v69
	s_waitcnt lgkmcnt(0)
	v_mfma_f32_16x16x32_bf16 v[18:21], v[18:21], v[10:13], 0
	s_nop 1
	v_cndmask_b32_e64 v42, v223, v42, s[52:53]
	v_cndmask_b32_e64 v43, v223, v43, s[56:57]
	v_cndmask_b32_e64 v44, v223, v44, s[58:59]
	v_mfma_f32_16x16x32_bf16 v[38:41], v[22:25], v[14:17], v[18:21]
	ds_read_b128 v[22:25], v70 offset:64
	v_cndmask_b32_e64 v45, v223, v45, s[60:61]
	s_nop 0
	ds_read_b128 v[18:21], v70
	s_waitcnt lgkmcnt(0)
	v_mfma_f32_16x16x32_bf16 v[18:21], v[18:21], v[10:13], 0
	s_nop 1
	v_cndmask_b32_e64 v38, v223, v38, s[62:63]
	v_cndmask_b32_e64 v39, v223, v39, s[64:65]
	v_cndmask_b32_e64 v40, v223, v40, s[66:67]
	v_mfma_f32_16x16x32_bf16 v[34:37], v[22:25], v[14:17], v[18:21]
	ds_read_b128 v[22:25], v71 offset:64
	v_cndmask_b32_e64 v41, v223, v41, s[68:69]
	s_nop 0
	ds_read_b128 v[18:21], v71
	s_waitcnt lgkmcnt(0)
	v_mfma_f32_16x16x32_bf16 v[18:21], v[18:21], v[10:13], 0
	s_nop 1
	v_cndmask_b32_e64 v34, v223, v34, s[70:71]
	v_cndmask_b32_e64 v35, v223, v35, s[72:73]
	v_cndmask_b32_e64 v36, v223, v36, s[74:75]
	v_mfma_f32_16x16x32_bf16 v[30:33], v[22:25], v[14:17], v[18:21]
	ds_read_b128 v[22:25], v72 offset:64
	v_cndmask_b32_e64 v37, v223, v37, s[76:77]
	s_nop 0
	ds_read_b128 v[18:21], v72
	s_waitcnt lgkmcnt(0)
	v_mfma_f32_16x16x32_bf16 v[18:21], v[18:21], v[10:13], 0
	s_nop 1
	v_cndmask_b32_e64 v30, v223, v30, s[78:79]
	v_cndmask_b32_e64 v31, v223, v31, s[80:81]
	v_cndmask_b32_e64 v32, v223, v32, s[82:83]
	v_mfma_f32_16x16x32_bf16 v[26:29], v[22:25], v[14:17], v[18:21]
	ds_read_b128 v[22:25], v73 offset:64
	v_cndmask_b32_e64 v33, v223, v33, s[84:85]
	s_nop 0
	ds_read_b128 v[18:21], v73
	s_waitcnt lgkmcnt(0)
	v_mfma_f32_16x16x32_bf16 v[18:21], v[18:21], v[10:13], 0
	s_nop 1
	v_cndmask_b32_e64 v26, v223, v26, s[86:87]
	v_cndmask_b32_e64 v27, v223, v27, s[88:89]
	v_cndmask_b32_e64 v28, v223, v28, s[90:91]
	v_mfma_f32_16x16x32_bf16 v[22:25], v[22:25], v[14:17], v[18:21]
	v_cndmask_b32_e64 v29, v223, v29, s[92:93]
	s_nop 1
	ds_read_b128 v[18:21], v74
	s_waitcnt lgkmcnt(0)
	v_mfma_f32_16x16x32_bf16 v[18:21], v[18:21], v[10:13], 0
	s_nop 1
	v_cndmask_b32_e64 v23, v223, v23, s[96:97]
	v_cndmask_b32_e64 v24, v223, v24, s[36:37]
	v_cndmask_b32_e64 v25, v223, v25, s[20:21]
	v_mfma_f32_16x16x32_bf16 v[18:21], v[76:79], v[14:17], v[18:21]
	ds_read_b128 v[76:79], v75
	s_waitcnt lgkmcnt(0)
	v_mfma_f32_16x16x32_bf16 v[10:13], v[76:79], v[10:13], 0
	ds_read_b128 v[76:79], v75 offset:64
	s_waitcnt lgkmcnt(0)
	v_mfma_f32_16x16x32_bf16 v[10:13], v[76:79], v[14:17], v[10:13]
	v_cndmask_b32_e64 v76, v223, v22, s[94:95]
	v_cndmask_b32_e64 v22, v223, v18, s[4:5]
	v_cndmask_b32_e64 v18, v223, v19, s[6:7]
	v_cndmask_b32_e64 v17, v223, v20, s[8:9]
	v_cndmask_b32_e64 v16, v223, v21, s[10:11]
	s_nop 1
	v_cndmask_b32_e64 v11, v223, v11, s[14:15]
	v_cndmask_b32_e64 v20, v223, v13, s[18:19]
	s_waitcnt vmcnt(0)
	v_max3_f32 v15, v86, v46, v47
	v_max3_f32 v15, v15, v48, v49
	v_max3_f32 v15, v15, v50, v51
	v_max3_f32 v15, v15, v52, v53
	v_max3_f32 v15, v15, v42, v43
	v_max3_f32 v15, v15, v44, v45
	v_max3_f32 v15, v15, v38, v39
	v_max3_f32 v15, v15, v40, v41
	v_max3_f32 v15, v15, v34, v35
	v_max3_f32 v15, v15, v36, v37
	v_max3_f32 v15, v15, v30, v31
	v_max3_f32 v15, v15, v32, v33
	v_max3_f32 v15, v15, v26, v27
	v_max3_f32 v15, v15, v28, v29
	v_max3_f32 v15, v15, v76, v23
	v_max3_f32 v15, v15, v24, v25
	v_max3_f32 v15, v15, v22, v18
	v_max3_f32 v19, v15, v17, v16
	v_cndmask_b32_e64 v15, v223, v10, s[12:13]
	v_max3_f32 v19, v19, v15, v11
	v_cndmask_b32_e64 v10, v223, v12, s[16:17]
	v_max3_f32 v12, v19, v10, v20
	ds_bpermute_b32 v13, v64, v12
	s_waitcnt lgkmcnt(0)
	v_max_f32_e32 v13, v13, v13
	v_max_f32_e32 v12, v12, v13
	ds_bpermute_b32 v13, v65, v12
	s_waitcnt lgkmcnt(0)
	v_max_f32_e32 v13, v13, v13
	v_max_f32_e32 v19, v12, v13
	v_sub_f32_e32 v12, v46, v19
	v_mul_f32_e32 v12, 0x3fb8aa3b, v12
	v_sub_f32_e32 v13, v47, v19
	v_exp_f32_e32 v12, v12
	v_mul_f32_e32 v13, 0x3fb8aa3b, v13
	v_sub_f32_e32 v46, v48, v19
	v_exp_f32_e32 v13, v13
	v_mul_f32_e32 v46, 0x3fb8aa3b, v46
	v_sub_f32_e32 v47, v49, v19
	v_exp_f32_e32 v46, v46
	v_mul_f32_e32 v47, 0x3fb8aa3b, v47
	v_sub_f32_e32 v48, v50, v19
	v_exp_f32_e32 v47, v47
	v_mul_f32_e32 v48, 0x3fb8aa3b, v48
	v_sub_f32_e32 v49, v51, v19
	v_add_f32_e32 v21, 0, v12
	v_exp_f32_e32 v48, v48
	v_mul_f32_e32 v49, 0x3fb8aa3b, v49
	v_sub_f32_e32 v50, v52, v19
	v_add_f32_e32 v21, v13, v21
	v_exp_f32_e32 v49, v49
	v_mul_f32_e32 v50, 0x3fb8aa3b, v50
	v_sub_f32_e32 v51, v53, v19
	v_add_f32_e32 v21, v46, v21
	v_exp_f32_e32 v50, v50
	v_mul_f32_e32 v51, 0x3fb8aa3b, v51
	v_sub_f32_e32 v42, v42, v19
	v_add_f32_e32 v21, v47, v21
	v_exp_f32_e32 v51, v51
	v_mul_f32_e32 v42, 0x3fb8aa3b, v42
	v_sub_f32_e32 v43, v43, v19
	v_add_f32_e32 v21, v48, v21
	v_exp_f32_e32 v42, v42
	v_mul_f32_e32 v43, 0x3fb8aa3b, v43
	v_sub_f32_e32 v44, v44, v19
	v_add_f32_e32 v21, v49, v21
	v_exp_f32_e32 v43, v43
	v_mul_f32_e32 v44, 0x3fb8aa3b, v44
	v_sub_f32_e32 v45, v45, v19
	v_add_f32_e32 v21, v50, v21
	v_exp_f32_e32 v44, v44
	v_mul_f32_e32 v45, 0x3fb8aa3b, v45
	v_sub_f32_e32 v38, v38, v19
	v_add_f32_e32 v21, v51, v21
	v_exp_f32_e32 v45, v45
	v_mul_f32_e32 v38, 0x3fb8aa3b, v38
	v_sub_f32_e32 v39, v39, v19
	v_add_f32_e32 v21, v42, v21
	v_exp_f32_e32 v38, v38
	v_mul_f32_e32 v39, 0x3fb8aa3b, v39
	v_sub_f32_e32 v40, v40, v19
	v_add_f32_e32 v21, v43, v21
	v_exp_f32_e32 v39, v39
	v_mul_f32_e32 v40, 0x3fb8aa3b, v40
	v_sub_f32_e32 v41, v41, v19
	v_add_f32_e32 v21, v44, v21
	v_exp_f32_e32 v40, v40
	v_mul_f32_e32 v41, 0x3fb8aa3b, v41
	v_sub_f32_e32 v34, v34, v19
	v_add_f32_e32 v21, v45, v21
	v_exp_f32_e32 v41, v41
	v_mul_f32_e32 v34, 0x3fb8aa3b, v34
	v_sub_f32_e32 v35, v35, v19
	v_add_f32_e32 v21, v38, v21
	v_exp_f32_e32 v34, v34
	v_mul_f32_e32 v35, 0x3fb8aa3b, v35
	v_sub_f32_e32 v36, v36, v19
	v_add_f32_e32 v21, v39, v21
	v_exp_f32_e32 v35, v35
	v_mul_f32_e32 v36, 0x3fb8aa3b, v36
	v_sub_f32_e32 v37, v37, v19
	v_add_f32_e32 v21, v40, v21
	v_exp_f32_e32 v36, v36
	v_mul_f32_e32 v37, 0x3fb8aa3b, v37
	v_sub_f32_e32 v30, v30, v19
	v_add_f32_e32 v21, v41, v21
	v_exp_f32_e32 v37, v37
	v_mul_f32_e32 v30, 0x3fb8aa3b, v30
	v_sub_f32_e32 v31, v31, v19
	v_add_f32_e32 v21, v34, v21
	v_exp_f32_e32 v30, v30
	v_mul_f32_e32 v31, 0x3fb8aa3b, v31
	v_sub_f32_e32 v32, v32, v19
	v_add_f32_e32 v21, v35, v21
	v_exp_f32_e32 v31, v31
	v_mul_f32_e32 v32, 0x3fb8aa3b, v32
	v_sub_f32_e32 v33, v33, v19
	v_add_f32_e32 v21, v36, v21
	v_exp_f32_e32 v32, v32
	v_mul_f32_e32 v33, 0x3fb8aa3b, v33
	v_sub_f32_e32 v26, v26, v19
	v_add_f32_e32 v21, v37, v21
	v_exp_f32_e32 v33, v33
	v_mul_f32_e32 v26, 0x3fb8aa3b, v26
	v_sub_f32_e32 v27, v27, v19
	v_add_f32_e32 v21, v30, v21
	v_exp_f32_e32 v26, v26
	v_mul_f32_e32 v27, 0x3fb8aa3b, v27
	v_sub_f32_e32 v28, v28, v19
	v_add_f32_e32 v21, v31, v21
	v_exp_f32_e32 v27, v27
	v_mul_f32_e32 v28, 0x3fb8aa3b, v28
	v_sub_f32_e32 v29, v29, v19
	v_sub_f32_e32 v23, v23, v19
	v_add_f32_e32 v21, v32, v21
	v_exp_f32_e32 v28, v28
	v_mul_f32_e32 v29, 0x3fb8aa3b, v29
	v_sub_f32_e32 v52, v76, v19
	v_mul_f32_e32 v23, 0x3fb8aa3b, v23
	v_add_f32_e32 v21, v33, v21
	v_exp_f32_e32 v29, v29
	v_mul_f32_e32 v52, 0x3fb8aa3b, v52
	v_exp_f32_e32 v53, v23
	v_sub_f32_e32 v23, v24, v19
	v_add_f32_e32 v21, v26, v21
	v_exp_f32_e32 v52, v52
	v_mul_f32_e32 v23, 0x3fb8aa3b, v23
	v_add_f32_e32 v21, v27, v21
	v_exp_f32_e32 v76, v23
	v_sub_f32_e32 v23, v25, v19
	v_add_f32_e32 v21, v28, v21
	v_mul_f32_e32 v23, 0x3fb8aa3b, v23
	v_sub_f32_e32 v22, v22, v19
	v_add_f32_e32 v21, v29, v21
	v_exp_f32_e32 v25, v23
	v_mul_f32_e32 v22, 0x3fb8aa3b, v22
	v_sub_f32_e32 v18, v18, v19
	v_add_f32_e32 v21, v52, v21
	v_exp_f32_e32 v77, v22
	v_mul_f32_e32 v18, 0x3fb8aa3b, v18
	v_sub_f32_e32 v17, v17, v19
	v_add_f32_e32 v21, v53, v21
	v_exp_f32_e32 v78, v18
	v_mul_f32_e32 v17, 0x3fb8aa3b, v17
	v_sub_f32_e32 v16, v16, v19
	v_add_f32_e32 v21, v76, v21
	v_exp_f32_e32 v79, v17
	v_mul_f32_e32 v16, 0x3fb8aa3b, v16
	v_sub_f32_e32 v15, v15, v19
	v_add_f32_e32 v21, v25, v21
	v_exp_f32_e32 v80, v16
	v_mul_f32_e32 v15, 0x3fb8aa3b, v15
	v_sub_f32_e32 v11, v11, v19
	v_add_f32_e32 v21, v77, v21
	v_exp_f32_e32 v81, v15
	v_mul_f32_e32 v11, 0x3fb8aa3b, v11
	v_sub_f32_e32 v10, v10, v19
	v_add_f32_e32 v18, v78, v21
	v_exp_f32_e32 v82, v11
	v_mul_f32_e32 v10, 0x3fb8aa3b, v10
	v_add_f32_e32 v17, v79, v18
	v_exp_f32_e32 v83, v10
	v_add_f32_e32 v16, v80, v17
	v_add_f32_e32 v15, v81, v16
	v_add_f32_e32 v11, v82, v15
	v_add_f32_e32 v10, v83, v11
	v_sub_f32_e32 v11, v20, v19
	v_mul_f32_e32 v11, 0x3fb8aa3b, v11
	v_exp_f32_e32 v84, v11
	s_nop 0
	v_add_f32_e32 v10, v84, v10
	ds_bpermute_b32 v11, v64, v10
	s_waitcnt lgkmcnt(0)
	v_add_f32_e32 v10, v10, v11
	ds_bpermute_b32 v11, v65, v10
	s_waitcnt lgkmcnt(0)
	v_add_f32_e32 v10, v10, v11
	v_sub_f32_e32 v11, v86, v19
	v_mul_f32_e32 v11, 0x3fb8aa3b, v11
	v_exp_f32_e32 v11, v11
	s_nop 0
	v_add_f32_e32 v10, v11, v10
	v_div_scale_f32 v11, vcc, v10, v10, 1.0
	v_rcp_f32_e32 v14, v11
	s_nop 0
	v_fma_f32 v15, -v11, v14, 1.0
	v_fmac_f32_e32 v14, v15, v14
	v_div_scale_f32 v15, vcc, 1.0, v10, 1.0
	v_mul_f32_e32 v16, v15, v14
	v_fma_f32 v17, -v11, v16, v15
	v_fmac_f32_e32 v16, v17, v14
	v_fma_f32 v11, -v11, v16, v15
	v_div_fmas_f32 v11, v11, v14, v16
	v_div_fixup_f32 v85, v11, v10, 1.0
	v_mul_f32_e32 v10, v12, v85
	v_mul_f32_e32 v11, v13, v85
	v_cvt_pk_bf16_f32 v10, v10, v11
	v_mul_f32_e32 v11, v46, v85
	v_mul_f32_e32 v12, v47, v85
	v_cvt_pk_bf16_f32 v11, v11, v12
	v_mul_f32_e32 v12, v48, v85
	v_mul_f32_e32 v13, v49, v85
	v_cvt_pk_bf16_f32 v12, v12, v13
	v_mul_f32_e32 v13, v50, v85
	v_mul_f32_e32 v14, v51, v85
	v_cvt_pk_bf16_f32 v13, v13, v14
	v_mul_f32_e32 v14, v42, v85
	v_mul_f32_e32 v15, v43, v85
	v_cvt_pk_bf16_f32 v14, v14, v15
	v_mul_f32_e32 v15, v44, v85
	v_mul_f32_e32 v16, v45, v85
	v_cvt_pk_bf16_f32 v15, v15, v16
	v_mul_f32_e32 v16, v38, v85
	v_mul_f32_e32 v17, v39, v85
	v_cvt_pk_bf16_f32 v16, v16, v17
	v_mul_f32_e32 v17, v40, v85
	v_mul_f32_e32 v18, v41, v85
	v_cvt_pk_bf16_f32 v17, v17, v18
	v_mul_f32_e32 v18, v34, v85
	v_mul_f32_e32 v19, v35, v85
	v_cvt_pk_bf16_f32 v18, v18, v19
	v_mul_f32_e32 v19, v36, v85
	v_mul_f32_e32 v20, v37, v85
	v_cvt_pk_bf16_f32 v19, v19, v20
	v_mul_f32_e32 v20, v30, v85
	v_mul_f32_e32 v21, v31, v85
	v_cvt_pk_bf16_f32 v20, v20, v21
	v_mul_f32_e32 v21, v32, v85
	v_mul_f32_e32 v22, v33, v85
	v_cvt_pk_bf16_f32 v21, v21, v22
	v_mul_f32_e32 v22, v26, v85
	v_mul_f32_e32 v23, v27, v85
	v_cvt_pk_bf16_f32 v22, v22, v23
	v_mul_f32_e32 v23, v28, v85
	v_mul_f32_e32 v24, v29, v85
	v_cvt_pk_bf16_f32 v23, v23, v24
	v_mul_f32_e32 v24, v52, v85
	v_mul_f32_e32 v26, v53, v85
	v_cvt_pk_bf16_f32 v24, v24, v26
	v_mul_f32_e32 v26, v76, v85
	v_mul_f32_e32 v25, v25, v85
	v_cvt_pk_bf16_f32 v25, v26, v25
	v_mul_f32_e32 v26, v77, v85
	v_mul_f32_e32 v27, v78, v85
	v_cvt_pk_bf16_f32 v26, v26, v27
	v_mul_f32_e32 v27, v79, v85
	v_mul_f32_e32 v28, v80, v85
	v_cvt_pk_bf16_f32 v27, v27, v28
	v_mul_f32_e32 v28, v81, v85
	v_mul_f32_e32 v29, v82, v85
	v_cvt_pk_bf16_f32 v28, v28, v29
	v_mul_f32_e32 v29, v83, v85
	v_add_u32_e32 v40, 0x9000, v0
	v_mul_f32_e32 v30, v84, v85
	v_cvt_pk_bf16_f32 v29, v29, v30
	ds_read2_b64 v[32:35], v40 offset1:4
	ds_read2_b64 v[36:39], v40 offset0:8 offset1:12
	s_waitcnt lgkmcnt(1)
	v_mfma_f32_16x16x32_bf16 v[32:35], v[32:35], v[10:13], 0
	v_lshl_add_u64 v[30:31], v[58:59], 0, s[28:29]
	s_add_u32 s28, s28, 0x80
	s_addc_u32 s29, s29, 0
	s_waitcnt lgkmcnt(0)
	v_mfma_f32_16x16x32_bf16 v[32:35], v[36:39], v[14:17], v[32:35]
	ds_read2_b64 v[36:39], v40 offset0:16 offset1:20
	s_add_u32 s2, s2, 4
	s_addc_u32 s3, s3, 0
	s_waitcnt lgkmcnt(0)
	v_mfma_f32_16x16x32_bf16 v[32:35], v[36:39], v[18:21], v[32:35]
	ds_read2_b64 v[36:39], v40 offset0:24 offset1:28
	s_cmpk_lg_i32 s28, 0x200
	s_waitcnt lgkmcnt(0)
	v_mfma_f32_16x16x32_bf16 v[32:35], v[36:39], v[22:25], v[32:35]
	ds_read2_b64 v[36:39], v40 offset0:32 offset1:36
	v_add_u32_e32 v40, 0xb000, v0
	s_waitcnt lgkmcnt(0)
	v_mfma_f32_16x16x32_bf16 v[32:35], v[36:39], v[26:29], v[32:35]
	v_lshlrev_b32_e32 v36, 16, v62
	s_nop 6
	v_mul_f32_e32 v32, v32, v36
	v_and_b32_e32 v36, 0xffff0000, v62
	v_mul_f32_e32 v33, v33, v36
	v_cvt_pk_bf16_f32 v32, v32, v33
	v_lshlrev_b32_e32 v33, 16, v63
	v_mul_f32_e32 v33, v34, v33
	v_and_b32_e32 v34, 0xffff0000, v63
	v_mul_f32_e32 v34, v35, v34
	v_cvt_pk_bf16_f32 v33, v33, v34
	global_store_dwordx2 v[30:31], v[32:33], off offset:-64
	ds_read2_b64 v[32:35], v40 offset0:32 offset1:36
	ds_read2_b64 v[36:39], v40 offset0:40 offset1:44
	s_waitcnt lgkmcnt(1)
	v_mfma_f32_16x16x32_bf16 v[32:35], v[32:35], v[10:13], 0
	s_waitcnt lgkmcnt(0)
	v_mfma_f32_16x16x32_bf16 v[32:35], v[36:39], v[14:17], v[32:35]
	ds_read2_b64 v[36:39], v40 offset0:48 offset1:52
	s_waitcnt lgkmcnt(0)
	v_mfma_f32_16x16x32_bf16 v[32:35], v[36:39], v[18:21], v[32:35]
	ds_read2_b64 v[36:39], v40 offset0:56 offset1:60
	s_waitcnt lgkmcnt(0)
	v_mfma_f32_16x16x32_bf16 v[32:35], v[36:39], v[22:25], v[32:35]
	ds_read2_b64 v[36:39], v40 offset0:64 offset1:68
	v_add_u32_e32 v40, 0xd000, v0
	s_waitcnt lgkmcnt(0)
	v_mfma_f32_16x16x32_bf16 v[32:35], v[36:39], v[26:29], v[32:35]
	v_mov_b32_e32 v36, v88
	v_mov_b32_e32 v37, v89
	v_lshlrev_b32_e32 v38, 16, v36
	v_and_b32_e32 v36, 0xffff0000, v36
	s_nop 3
	v_mul_f32_e32 v32, v32, v38
	v_mul_f32_e32 v33, v33, v36
	v_cvt_pk_bf16_f32 v32, v32, v33
	v_lshlrev_b32_e32 v33, 16, v37
	v_mul_f32_e32 v33, v34, v33
	v_and_b32_e32 v34, 0xffff0000, v37
	v_mul_f32_e32 v34, v35, v34
	v_cvt_pk_bf16_f32 v33, v33, v34
	global_store_dwordx2 v[30:31], v[32:33], off offset:-32
	ds_read2_b64 v[32:35], v40 offset0:64 offset1:68
	ds_read2_b64 v[36:39], v40 offset0:72 offset1:76
	s_waitcnt lgkmcnt(1)
	v_mfma_f32_16x16x32_bf16 v[32:35], v[32:35], v[10:13], 0
	s_waitcnt lgkmcnt(0)
	v_mfma_f32_16x16x32_bf16 v[32:35], v[36:39], v[14:17], v[32:35]
	ds_read2_b64 v[36:39], v40 offset0:80 offset1:84
	s_waitcnt lgkmcnt(0)
	v_mfma_f32_16x16x32_bf16 v[32:35], v[36:39], v[18:21], v[32:35]
	ds_read2_b64 v[36:39], v40 offset0:88 offset1:92
	s_waitcnt lgkmcnt(0)
	v_mfma_f32_16x16x32_bf16 v[32:35], v[36:39], v[22:25], v[32:35]
	ds_read2_b64 v[36:39], v40 offset0:96 offset1:100
	s_waitcnt lgkmcnt(0)
	v_mfma_f32_16x16x32_bf16 v[32:35], v[36:39], v[26:29], v[32:35]
	v_mov_b32_e32 v36, v90
	v_mov_b32_e32 v37, v91
	v_lshlrev_b32_e32 v38, 16, v36
	v_and_b32_e32 v36, 0xffff0000, v36
	s_nop 3
	v_mul_f32_e32 v32, v32, v38
	v_mul_f32_e32 v33, v33, v36
	v_cvt_pk_bf16_f32 v32, v32, v33
	v_lshlrev_b32_e32 v33, 16, v37
	v_mul_f32_e32 v33, v34, v33
	v_and_b32_e32 v34, 0xffff0000, v37
	v_mul_f32_e32 v34, v35, v34
	v_cvt_pk_bf16_f32 v33, v33, v34
	v_add_u32_e32 v36, 0xf000, v0
	global_store_dwordx2 v[30:31], v[32:33], off
	ds_read2_b64 v[32:35], v36 offset0:96 offset1:100
	s_waitcnt lgkmcnt(0)
	v_mfma_f32_16x16x32_bf16 v[10:13], v[32:35], v[10:13], 0
	ds_read2_b64 v[32:35], v36 offset0:104 offset1:108
	s_waitcnt lgkmcnt(0)
	v_mfma_f32_16x16x32_bf16 v[10:13], v[32:35], v[14:17], v[10:13]
	ds_read2_b64 v[14:17], v36 offset0:112 offset1:116
	s_waitcnt lgkmcnt(0)
	v_mfma_f32_16x16x32_bf16 v[10:13], v[14:17], v[18:21], v[10:13]
	ds_read2_b64 v[14:17], v36 offset0:120 offset1:124
	s_waitcnt lgkmcnt(0)
	v_mfma_f32_16x16x32_bf16 v[10:13], v[14:17], v[22:25], v[10:13]
	ds_read2_b64 v[14:17], v36 offset0:128 offset1:132
	s_waitcnt lgkmcnt(0)
	v_mfma_f32_16x16x32_bf16 v[10:13], v[14:17], v[26:29], v[10:13]
	v_mov_b32_e32 v14, v92
	v_mov_b32_e32 v15, v93
	v_lshlrev_b32_e32 v16, 16, v14
	v_and_b32_e32 v14, 0xffff0000, v14
	s_nop 3
	v_mul_f32_e32 v10, v10, v16
	v_mul_f32_e32 v11, v11, v14
	v_cvt_pk_bf16_f32 v10, v10, v11
	v_lshlrev_b32_e32 v11, 16, v15
	v_mul_f32_e32 v11, v12, v11
	v_and_b32_e32 v12, 0xffff0000, v15
	v_mul_f32_e32 v12, v13, v12
	v_cvt_pk_bf16_f32 v11, v11, v12
	global_store_dwordx2 v[30:31], v[10:11], off offset:32
	v_mov_b64_e32 v[12:13], v[8:9]
	v_mov_b64_e32 v[16:17], v[4:5]
	v_mov_b64_e32 v[10:11], v[6:7]
	v_mov_b64_e32 v[14:15], v[2:3]
	s_cbranch_scc0 .LBB0_816
